# X1 work queue: next item index fetched (atomic) right after the current index is known so its round trip overlaps the item work (on v63)
# baseline (speedup 1.0000x reference)
; DI void dn_prep_item(CParams& p, int layer, int it, int S, char* lds) {
;     ...
;   const int NC = S / 64;
;   const int ch = it % NC, bh = it / NC, h = bh & 3, b = bh >> 2;
; __global__ void __launch_bounds__(256, 2) mega(Params pk) {
;     ...
;       {
;         PP_
;         int* c0 = (int*)(p.ws + OFF_CNT) + (layer * 2 + grp) * 4;
;         for (;;) {
;           __syncthreads();
;           if (threadIdx.x == 0) s_item = atomicAdd(c0, 1);
;           __syncthreads();
;           const int it = __builtin_amdgcn_readfirstlane(s_item);
;           if (it >= 2048) break;
.LBB0_460:
	v_writelane_b32 v243, s64, 52
	s_nop 1
	v_writelane_b32 v243, s65, 53
	v_writelane_b32 v243, s62, 54
	s_nop 1
	v_writelane_b32 v243, s63, 55
	v_writelane_b32 v243, s60, 56
	s_nop 1
	v_writelane_b32 v243, s61, 57
	s_or_b64 exec, exec, s[0:1]
	s_mov_b64 s[0:1], s[94:95]
	s_waitcnt lgkmcnt(0)
	s_barrier
	s_load_dwordx2 s[42:43], s[0:1], 0x100
	v_readlane_b32 s6, v243, 40
	v_writelane_b32 v243, s58, 58
	s_or_b32 s91, s58, s6
	s_lshl_b32 s28, s91, 2
	s_lshl_b64 s[8:9], s[28:29], 2
	v_writelane_b32 v243, s59, 59
	s_waitcnt lgkmcnt(0)
	s_add_u32 s6, s42, s8
	v_writelane_b32 v243, s8, 60
	s_addc_u32 s7, s43, s9
	s_add_u32 s94, s6, 0x3f00000
	s_addc_u32 s95, s7, 0
	s_lshr_b32 s88, s86, 6
	v_cvt_f32_u32_e32 v0, s88
	v_writelane_b32 v243, s9, 61
	v_rcp_iflag_f32_e32 v0, v0
	v_readlane_b32 s6, v243, 52
	v_readlane_b32 s7, v243, 53
	s_and_b64 s[6:7], s[6:7], exec
	v_mul_f32_e32 v0, 0x4f7ffffe, v0
	v_cvt_u32_f32_e32 v0, v0
	s_cselect_b32 s89, 14, 11
	s_cselect_b32 s90, 8, 5
	s_add_u32 s34, s42, 0x1e000000
	s_addc_u32 s35, s43, 0
	s_add_u32 s24, s42, 0x1a000000
	s_addc_u32 s25, s43, 0
	s_sub_i32 s6, 0, s88
	v_readfirstlane_b32 s7, v0
	s_mul_i32 s6, s6, s7
	s_mul_hi_u32 s6, s7, s6
	s_add_i32 s92, s7, s6
	s_and_saveexec_b64 s[100:101], s[4:5]
	v_mov_b32_e32 v249, 1
	global_atomic_add v248, v1, v249, s[94:95] sc0
	s_mov_b64 exec, s[100:101]
	s_branch .LBB0_463

; __global__ void __launch_bounds__(256, 2) mega(Params pk) {
;     ...
;         for (;;) {
;           __syncthreads();
;           if (threadIdx.x == 0) s_item = atomicAdd(c0, 1);
.LBB0_463:
	s_barrier
	s_and_saveexec_b64 s[6:7], s[4:5]
	s_cbranch_execz .LBB0_467
	s_mov_b64 s[38:39], exec
	v_mbcnt_lo_u32_b32 v0, s38, 0
	v_mbcnt_hi_u32_b32 v0, s39, v0
	v_cmp_eq_u32_e32 vcc, 0, v0
	s_and_saveexec_b64 s[8:9], vcc
	s_cbranch_execz .LBB0_466
	s_bcnt1_i32_b64 s28, s[38:39]
	v_mov_b32_e32 v2, s28
	s_waitcnt vmcnt(0)
	v_mov_b32_e32 v2, v248

; DI void dn_prep_item(CParams& p, int layer, int it, int S, char* lds) {
;     ...
;   const int ch = it % NC, bh = it / NC, h = bh & 3, b = bh >> 2;
;   const int tokbase = b * S, s0 = ch * 64;
;   const bf16_t* PR = (const bf16_t*)(p.ws + OFF_PR);
;   const float* AB = (const float*)(p.ws + OFF_AB);
;   bf16_t* QKg = (bf16_t*)(p.ws + DN_QK_OFF) + ((size_t)bh * NC + ch) * 8192;
;   bf16_t* raw = (bf16_t*)lds;
;   float* convw = (float*)(lds + 27200);
;   float* RU = (float*)lds;
;   float* RW = (float*)(lds + 16384);
;   float* Am = (float*)(lds + 32768);
;   bf16_t* Kimg = (bf16_t*)(lds + 50176);
;   bf16_t* Qimg = (bf16_t*)(lds + 59392);
;   float* gcs = (float*)(lds + 68608);
;   float* betas = gcs + 128;
;   const float* cw = p.dn_conv + (size_t)layer * 5 * 768;
;   {
;     u32x4 rawreg[7];
;     float cwr[4];
; #pragma unroll
;     for (int k = 0; k < 7; ++k) {
;       const int ci = tid + 256 * k;
;       const int rr = ci / 24, c = ci % 24, seg = c >> 3, c8 = c & 7;
;       const int s = s0 + rr - 2;
;       rawreg[k] = u32x4{0u, 0u, 0u, 0u};
;       if (ci < 68 * 24 && s >= 0 && s < S)
;         rawreg[k] = *(const u32x4*)(PR + (size_t)(tokbase + s) * NPR + C_DNQKV + seg * 256 + h * 64 + c8 * 8);
; __global__ void __launch_bounds__(256, 2) mega(Params pk) {
;     ...
;           __syncthreads();
;           const int it = __builtin_amdgcn_readfirstlane(s_item);
;           if (it >= 2048) break;
;           dn_prep_item(p, layer, it, S, lds);
.LBB0_467:
	s_or_b64 exec, exec, s[6:7]
	s_waitcnt lgkmcnt(0)
	s_barrier
	flat_load_dword v0, v[218:219] sc0 sc1
	s_waitcnt vmcnt(0)
	s_mov_b64 s[6:7], -1
	s_waitcnt lgkmcnt(0)
	v_readfirstlane_b32 s8, v0
	s_cmpk_gt_i32 s8, 0x7ff
	s_cbranch_scc1 .LBB0_462
	s_and_saveexec_b64 s[100:101], s[4:5]
	v_mov_b32_e32 v249, 1
	global_atomic_add v248, v1, v249, s[94:95] sc0
	s_mov_b64 exec, s[100:101]
	s_abs_i32 s7, s8
	s_mul_hi_u32 s9, s7, s92
	s_mul_i32 s28, s9, s88
	s_sub_i32 s7, s7, s28
	s_ashr_i32 s6, s8, 31
	s_add_i32 s28, s9, 1
	s_sub_i32 s38, s7, s88
	s_cmp_ge_u32 s7, s88
	s_cselect_b32 s9, s28, s9
	s_cselect_b32 s7, s38, s7
	s_add_i32 s28, s9, 1
	s_cmp_ge_u32 s7, s88
	s_cselect_b32 s7, s28, s9
	s_xor_b32 s7, s7, s6
	v_mov_b32 v0, 0
	s_sub_i32 s64, s7, s6
	v_add_u32_e32 v147, v0, v210
	s_mul_i32 s6, s64, s88
	v_mul_hi_i32 v35, v147, s17
	s_sub_i32 s38, s8, s6
	v_lshrrev_b32_e32 v36, 31, v35
	v_ashrrev_i32_e32 v0, 2, v35
	s_lshl_b32 s68, s38, 6
	v_add_u32_e32 v30, v0, v36
	s_ashr_i32 s6, s64, 2
	v_add_u32_e32 v2, s68, v30
	s_lshl_b32 s67, s6, s89
	v_add_u32_e32 v0, -2, v2
	s_movk_i32 s6, 0x660
	v_cmp_gt_i32_e64 s[44:45], s6, v147
	v_cmp_gt_i32_e64 s[46:47], s86, v0
	s_and_b32 s66, s64, 3
	v_cmp_lt_i32_e32 vcc, 1, v2
	s_and_b64 s[6:7], s[44:45], s[46:47]
	s_lshl_b32 s39, s66, 6
	s_and_b64 s[8:9], s[6:7], vcc
	v_mov_b32_e32 v2, 0
	v_mov_b32_e32 v6, 0
	v_mov_b32_e32 v7, 0
	v_mov_b32_e32 v8, 0
	v_mov_b32_e32 v9, 0
	s_and_saveexec_b64 s[6:7], s[8:9]
	s_cbranch_execz .LBB0_470
	v_lshrrev_b32_e32 v3, 2, v35
	v_add_u32_e32 v3, v3, v36
	v_mul_lo_u32 v3, v3, 24
	v_sub_u32_e32 v3, v147, v3
	v_add_u32_e32 v0, s67, v0
	v_mov_b64_e32 v[4:5], s[42:43]
	v_mad_i64_i32 v[4:5], s[8:9], v0, s16, v[4:5]
	v_lshlrev_b32_e32 v0, 5, v3
	v_and_b32_e32 v6, 0xffffff00, v0
	v_ashrrev_i32_e32 v7, 31, v6
	v_lshl_add_u64 v[4:5], v[6:7], 1, v[4:5]
	s_lshl_b32 s28, s39, 1
	v_lshlrev_b32_e32 v0, 4, v3
	v_lshl_add_u64 v[4:5], v[4:5], 0, s[28:29]
	v_and_b32_e32 v0, 0x70, v0
	v_lshl_add_u64 v[4:5], v[4:5], 0, v[0:1]
	v_add_co_u32_e32 v4, vcc, 0x8000000, v4
	s_nop 1
	v_addc_co_u32_e32 v5, vcc, 0, v5, vcc
	global_load_dwordx4 v[6:9], v[4:5], off offset:2304
